# v19 + at the projection/attention seam the XCD leader releases its XCD before the L2 write-back and cross-XCD arrive
# baseline (speedup 1.0000x reference)
; __device__ __forceinline__ unsigned xb_ld(unsigned* p)              { return __hip_atomic_load(p, __ATOMIC_RELAXED, __HIP_MEMORY_SCOPE_AGENT); }
; __device__ __forceinline__ unsigned xb_add(unsigned* p, unsigned v) { return __hip_atomic_fetch_add(p, v, __ATOMIC_RELAXED, __HIP_MEMORY_SCOPE_AGENT); }
; #define XB_SPIN(cond, bar) do { unsigned _sp = 0; while (cond) { __builtin_amdgcn_s_sleep(1); \
;     if ((++_sp & 255u) == 0u) { if (xb_ld(&(bar)[XB_TMO])) break; if (_sp > XB_SPIN_CAP) { atomicAdd(&(bar)[XB_TMO], 1u); break; } } } } while (0)
; __device__ __forceinline__ void xcd_barrier(const XcdBarrier& b, int tid) {
;     ...
;         const unsigned old = xb_add(&bar[XB_XSUB(b.x)], 1u);
;         const unsigned gen = old / nloc;
;         if (old + 1u == (gen + 1u) * nloc) {
;             __builtin_amdgcn_fence(__ATOMIC_RELEASE, "agent");
;             asm volatile("s_waitcnt vmcnt(0)" ::: "memory");
;             const unsigned og = xb_add(&bar[XB_TOP], 1u);
;             const unsigned tg = og / nx;
;             if (og + 1u == (tg + 1u) * nx) xb_add(&bar[XB_TOPGEN], 1u);
;             else XB_SPIN(xb_ld(&bar[XB_TOPGEN]) == tg, bar);
;             __builtin_amdgcn_fence(__ATOMIC_ACQUIRE, "agent");
;             xb_add(&bar[XB_XGEN(b.x)], 1u);
;             asm volatile("s_waitcnt vmcnt(0)" ::: "memory");
.LBB0_721:
	s_andn2_saveexec_b64 s[0:1], s[8:9]
	s_cbranch_execz .LBB0_741
	s_mov_b64 s[8:9], exec
	v_readlane_b32 s0, v248, 32
	s_nop 3
	s_cmp_eq_u32 s0, 1
	s_cbranch_scc0 .Lsplit3_noearly
	v_mov_b32_e32 v2, 0x2000
	v_mov_b32_e32 v3, 1
	global_atomic_add v2, v3, s[6:7] offset:1024
.Lsplit3_noearly:
	buffer_wbl2 sc1
	s_waitcnt lgkmcnt(0)
	s_waitcnt vmcnt(0)
	v_mbcnt_lo_u32_b32 v1, s8, 0
	v_mbcnt_hi_u32_b32 v1, s9, v1
	v_cmp_eq_u32_e32 vcc, 0, v1
	s_and_saveexec_b64 s[10:11], vcc
	s_cbranch_execz .LBB0_724
	s_bcnt1_i32_b64 s0, s[8:9]
	v_mov_b32_e32 v2, 0x3000
	v_mov_b32_e32 v3, s0
	global_atomic_add v2, v2, v3, s[40:41] offset:1024 sc0

; __device__ __forceinline__ unsigned xb_add(unsigned* p, unsigned v) { return __hip_atomic_fetch_add(p, v, __ATOMIC_RELAXED, __HIP_MEMORY_SCOPE_AGENT); }
; __device__ __forceinline__ void xcd_barrier(const XcdBarrier& b, int tid) {
;     ...
;             __builtin_amdgcn_fence(__ATOMIC_ACQUIRE, "agent");
;             xb_add(&bar[XB_XGEN(b.x)], 1u);
;             asm volatile("s_waitcnt vmcnt(0)" ::: "memory");
.LBB0_738:
	s_or_b64 exec, exec, s[8:9]
	s_mov_b64 s[8:9], exec
	v_mbcnt_lo_u32_b32 v0, s8, 0
	v_mbcnt_hi_u32_b32 v0, s9, v0
	v_cmp_eq_u32_e32 vcc, 0, v0
	s_waitcnt vmcnt(0)
	s_and_saveexec_b64 s[10:11], vcc
	s_cbranch_execz .LBB0_740
	v_readlane_b32 s0, v248, 32
	s_nop 3
	s_cmp_eq_u32 s0, 1
	s_cbranch_scc1 .LBB0_740
	s_bcnt1_i32_b64 s0, s[8:9]
	v_mov_b32_e32 v0, 0x2000
	v_mov_b32_e32 v1, s0
	global_atomic_add v0, v1, s[6:7] offset:1024
